# v43 padded by 52 bytes so downstream loop alignment mod 64 matches v41 (placement control)
# speedup vs baseline: 1.0042x; 1.0021x over previous
.LBB0_114:
	s_or_b64 exec, exec, s[26:27]
	v_lshl_add_u32 v106, s2, 6, v86
	v_ashrrev_i32_e32 v107, 31, v106
	v_lshlrev_b64 v[106:107], 13, v[106:107]
	v_lshl_add_u64 v[106:107], v[70:71], 0, v[106:107]
	global_load_dwordx4 v[60:63], v[106:107], off nt
	global_load_dwordx4 v[56:59], v[106:107], off offset:1024 nt
	global_load_dwordx4 v[52:55], v[106:107], off offset:2048 nt
	global_load_dwordx4 v[48:51], v[106:107], off offset:3072 nt
	v_add_co_u32_e32 v106, vcc, 0x1000, v106
	s_nop 1
	v_addc_co_u32_e32 v107, vcc, 0, v107, vcc
	global_load_dwordx4 v[44:47], v[106:107], off nt
	global_load_dwordx4 v[40:43], v[106:107], off offset:1024 nt
	global_load_dwordx4 v[36:39], v[106:107], off offset:2048 nt
	global_load_dwordx4 v[32:35], v[106:107], off offset:3072 nt
	s_and_saveexec_b64 s[26:27], s[4:5]
	s_cbranch_execz .LBB0_117
	s_mov_b32 s3, 0xd020
	v_add_u32_e32 v101, 0x0, v64
	v_ashrrev_i32_e32 v150, 1, v101
	v_lshlrev_b32_e32 v102, 2, v101
	v_and_b32_e32 v102, 4, v102
	v_mov_b64_e32 v[104:105], s[70:71]
	v_mad_i64_i32 v[104:105], s[36:37], v150, s3, v[104:105]
	v_lshlrev_b32_e32 v66, 2, v102
	v_lshl_add_u64 v[104:105], v[104:105], 0, v[66:67]
	v_add_co_u32_e32 v104, vcc, 0x9000, v104
	v_lshlrev_b32_e32 v150, 2, v150
	v_lshlrev_b32_e32 v102, 13, v102
	v_addc_co_u32_e32 v105, vcc, 0, v105, vcc
	global_load_dwordx4 v[110:113], v[104:105], off
	v_add3_u32 v150, 0, v150, v102
	v_add_u32_e32 v101, 0x200, v64
	v_ashrrev_i32_e32 v151, 1, v101
	v_lshlrev_b32_e32 v102, 2, v101
	v_and_b32_e32 v102, 4, v102
	v_mov_b64_e32 v[104:105], s[70:71]
	v_mad_i64_i32 v[104:105], s[36:37], v151, s3, v[104:105]
	v_lshlrev_b32_e32 v66, 2, v102
	v_lshl_add_u64 v[104:105], v[104:105], 0, v[66:67]
	v_add_co_u32_e32 v104, vcc, 0x9000, v104
	v_lshlrev_b32_e32 v151, 2, v151
	v_lshlrev_b32_e32 v102, 13, v102
	v_addc_co_u32_e32 v105, vcc, 0, v105, vcc
	global_load_dwordx4 v[114:117], v[104:105], off
	v_add3_u32 v151, 0, v151, v102
	v_add_u32_e32 v101, 0x400, v64
	v_ashrrev_i32_e32 v152, 1, v101
	v_lshlrev_b32_e32 v102, 2, v101
	v_and_b32_e32 v102, 4, v102
	v_mov_b64_e32 v[104:105], s[70:71]
	v_mad_i64_i32 v[104:105], s[36:37], v152, s3, v[104:105]
	v_lshlrev_b32_e32 v66, 2, v102
	v_lshl_add_u64 v[104:105], v[104:105], 0, v[66:67]
	v_add_co_u32_e32 v104, vcc, 0x9000, v104
	v_lshlrev_b32_e32 v152, 2, v152
	v_lshlrev_b32_e32 v102, 13, v102
	v_addc_co_u32_e32 v105, vcc, 0, v105, vcc
	global_load_dwordx4 v[118:121], v[104:105], off
	v_add3_u32 v152, 0, v152, v102
	v_add_u32_e32 v101, 0x600, v64
	v_ashrrev_i32_e32 v153, 1, v101
	v_lshlrev_b32_e32 v102, 2, v101
	v_and_b32_e32 v102, 4, v102
	v_mov_b64_e32 v[104:105], s[70:71]
	v_mad_i64_i32 v[104:105], s[36:37], v153, s3, v[104:105]
	v_lshlrev_b32_e32 v66, 2, v102
	v_lshl_add_u64 v[104:105], v[104:105], 0, v[66:67]
	v_add_co_u32_e32 v104, vcc, 0x9000, v104
	v_lshlrev_b32_e32 v153, 2, v153
	v_lshlrev_b32_e32 v102, 13, v102
	v_addc_co_u32_e32 v105, vcc, 0, v105, vcc
	global_load_dwordx4 v[122:125], v[104:105], off
	v_add3_u32 v153, 0, v153, v102
	v_add_u32_e32 v101, 0x800, v64
	v_ashrrev_i32_e32 v154, 1, v101
	v_lshlrev_b32_e32 v102, 2, v101
	v_and_b32_e32 v102, 4, v102
	v_mov_b64_e32 v[104:105], s[70:71]
	v_mad_i64_i32 v[104:105], s[36:37], v154, s3, v[104:105]
	v_lshlrev_b32_e32 v66, 2, v102
	v_lshl_add_u64 v[104:105], v[104:105], 0, v[66:67]
	v_add_co_u32_e32 v104, vcc, 0x9000, v104
	v_lshlrev_b32_e32 v154, 2, v154
	v_lshlrev_b32_e32 v102, 13, v102
	v_addc_co_u32_e32 v105, vcc, 0, v105, vcc
	global_load_dwordx4 v[126:129], v[104:105], off
	v_add3_u32 v154, 0, v154, v102
	v_add_u32_e32 v101, 0xa00, v64
	v_ashrrev_i32_e32 v155, 1, v101
	v_lshlrev_b32_e32 v102, 2, v101
	v_and_b32_e32 v102, 4, v102
	v_mov_b64_e32 v[104:105], s[70:71]
	v_mad_i64_i32 v[104:105], s[36:37], v155, s3, v[104:105]
	v_lshlrev_b32_e32 v66, 2, v102
	v_lshl_add_u64 v[104:105], v[104:105], 0, v[66:67]
	v_add_co_u32_e32 v104, vcc, 0x9000, v104
	v_lshlrev_b32_e32 v155, 2, v155
	v_lshlrev_b32_e32 v102, 13, v102
	v_addc_co_u32_e32 v105, vcc, 0, v105, vcc
	global_load_dwordx4 v[130:133], v[104:105], off
	v_add3_u32 v155, 0, v155, v102
	v_add_u32_e32 v101, 0xc00, v64
	v_ashrrev_i32_e32 v156, 1, v101
	v_lshlrev_b32_e32 v102, 2, v101
	v_and_b32_e32 v102, 4, v102
	v_mov_b64_e32 v[104:105], s[70:71]
	v_mad_i64_i32 v[104:105], s[36:37], v156, s3, v[104:105]
	v_lshlrev_b32_e32 v66, 2, v102
	v_lshl_add_u64 v[104:105], v[104:105], 0, v[66:67]
	v_add_co_u32_e32 v104, vcc, 0x9000, v104
	v_lshlrev_b32_e32 v156, 2, v156
	v_lshlrev_b32_e32 v102, 13, v102
	v_addc_co_u32_e32 v105, vcc, 0, v105, vcc
	global_load_dwordx4 v[134:137], v[104:105], off
	v_add3_u32 v156, 0, v156, v102
	v_add_u32_e32 v101, 0xe00, v64
	v_ashrrev_i32_e32 v157, 1, v101
	v_lshlrev_b32_e32 v102, 2, v101
	v_and_b32_e32 v102, 4, v102
	v_mov_b64_e32 v[104:105], s[70:71]
	v_mad_i64_i32 v[104:105], s[36:37], v157, s3, v[104:105]
	v_lshlrev_b32_e32 v66, 2, v102
	v_lshl_add_u64 v[104:105], v[104:105], 0, v[66:67]
	v_add_co_u32_e32 v104, vcc, 0x9000, v104
	v_lshlrev_b32_e32 v157, 2, v157
	v_lshlrev_b32_e32 v102, 13, v102
	v_addc_co_u32_e32 v105, vcc, 0, v105, vcc
	global_load_dwordx4 v[138:141], v[104:105], off
	v_add3_u32 v157, 0, v157, v102
	s_waitcnt vmcnt(7)
	ds_write2st64_b32 v150, v110, v111 offset0:64 offset1:96
	ds_write2st64_b32 v150, v112, v113 offset0:128 offset1:160
	s_waitcnt vmcnt(6)
	ds_write2st64_b32 v151, v114, v115 offset0:64 offset1:96
	ds_write2st64_b32 v151, v116, v117 offset0:128 offset1:160
	s_waitcnt vmcnt(5)
	ds_write2st64_b32 v152, v118, v119 offset0:64 offset1:96
	ds_write2st64_b32 v152, v120, v121 offset0:128 offset1:160
	s_waitcnt vmcnt(4)
	ds_write2st64_b32 v153, v122, v123 offset0:64 offset1:96
	ds_write2st64_b32 v153, v124, v125 offset0:128 offset1:160
	s_waitcnt vmcnt(3)
	ds_write2st64_b32 v154, v126, v127 offset0:64 offset1:96
	ds_write2st64_b32 v154, v128, v129 offset0:128 offset1:160
	s_waitcnt vmcnt(2)
	ds_write2st64_b32 v155, v130, v131 offset0:64 offset1:96
	ds_write2st64_b32 v155, v132, v133 offset0:128 offset1:160
	s_waitcnt vmcnt(1)
	ds_write2st64_b32 v156, v134, v135 offset0:64 offset1:96
	ds_write2st64_b32 v156, v136, v137 offset0:128 offset1:160
	s_waitcnt vmcnt(0)
	ds_write2st64_b32 v157, v138, v139 offset0:64 offset1:96
	ds_write2st64_b32 v157, v140, v141 offset0:128 offset1:160
	s_nop 0
	s_nop 0
	s_nop 0
	s_nop 0
	s_nop 0
	s_nop 0
	s_nop 0
	s_nop 0
	s_nop 0
	s_nop 0
	s_nop 0
	s_nop 0
	s_nop 0
